# P0: hand-written branch-free generation of the S5 weight tables W2/W1 with 16-byte stores (on top of two-pass KT, adaLN, attention edits)
# speedup vs baseline: 1.0200x; 1.0057x over previous
; __device__ __forceinline__ unsigned pk2(float lo, float hi) { typedef __bf16 bf16x2_t_ __attribute__((ext_vector_type(2))); f32x2 v = {lo, hi}; return __builtin_bit_cast(unsigned, __builtin_convertvector(v, bf16x2_t_)); }
; __device__ __forceinline__ f32x2 cmul(f32x2 a, f32x2 b) { return (f32x2){a.x * b.x - a.y * b.y, a.x * b.y + a.y * b.x}; }
; __global__ void __launch_bounds__(NTHR, 2) hymba_fwd(Params P) {
;     ...
;             bf16_t* w2 = W2 + (size_t)g * 256 * 384;
;             for (int idx = tid; idx < 256 * 192; idx += NTHR) { const int c = idx / 192, k = (idx % 192) * 2, t = c >> 4, p = c & 15; float v[2];
; #pragma unroll
;                 for (int e = 0; e < 2; ++e) { const int kk = k + e; float r;
;                     if (kk < 256) { const int s = kk >> 4, pp = kk & 15; r = (s <= t) ? KT[((t - s) * 16 + p) * 16 + pp] : 0.f; }
;                     else { const int n = (kk - 256) & 63; const f32x2 z = cmul(CCl[p * 64 + n], PW[(t + 1) * 64 + n]); r = (kk < 320) ? z.x : -z.y; }
;                     v[e] = r; }
;                 *(unsigned*)(w2 + (size_t)c * 384 + k) = pk2(v[0], v[1]); }
.LBB0_25:
	s_or_b64 exec, exec, s[4:5]
	s_waitcnt lgkmcnt(0)
	s_barrier
	s_mov_b64 s[4:5], exec
	s_mul_i32 s1, s10, 0x30000
	v_readlane_b32 s6, v255, 12
	s_mul_hi_u32 s0, s10, 0x30000
	s_add_u32 s6, s6, s1
	v_readlane_b32 s1, v255, 13
	s_addc_u32 s7, s1, s0
	s_lshl_b64 s[0:1], s[10:11], 17
	v_readlane_b32 s14, v255, 14
	s_add_u32 s14, s14, s0
	v_readlane_b32 s0, v255, 15
	s_addc_u32 s15, s0, s1
	v_lshrrev_b32_e32 v2, 1, v8
	v_and_b32_e32 v3, 1, v8
	v_lshrrev_b32_e32 v4, 4, v2
	v_and_b32_e32 v5, 15, v2
	v_mul_u32_u24_e32 v6, 0x300, v2
	v_lshl_add_u32 v6, v3, 8, v6
	v_lshlrev_b32_e32 v7, 3, v3
	v_sub_u32_e32 v9, v4, v7
	v_lshlrev_b32_e32 v10, 6, v5
	v_add_u32_e32 v10, 0x6200, v10
	v_subrev_u32_e32 v11, 0, v9
	v_cmp_le_i32_e32 vcc, 0, v11
	v_max_i32_e32 v11, 0, v11
	v_lshl_add_u32 v11, v11, 10, v10
	ds_read_b128 v[12:15], v11 offset:0
	ds_read_b128 v[16:19], v11 offset:16
	ds_read_b128 v[20:23], v11 offset:32
	ds_read_b128 v[24:27], v11 offset:48
	s_waitcnt lgkmcnt(0)
	v_cndmask_b32_e32 v12, 0, v12, vcc
	v_cndmask_b32_e32 v13, 0, v13, vcc
	v_cndmask_b32_e32 v14, 0, v14, vcc
	v_cndmask_b32_e32 v15, 0, v15, vcc
	v_cndmask_b32_e32 v16, 0, v16, vcc
	v_cndmask_b32_e32 v17, 0, v17, vcc
	v_cndmask_b32_e32 v18, 0, v18, vcc
	v_cndmask_b32_e32 v19, 0, v19, vcc
	v_cndmask_b32_e32 v20, 0, v20, vcc
	v_cndmask_b32_e32 v21, 0, v21, vcc
	v_cndmask_b32_e32 v22, 0, v22, vcc
	v_cndmask_b32_e32 v23, 0, v23, vcc
	v_cndmask_b32_e32 v24, 0, v24, vcc
	v_cndmask_b32_e32 v25, 0, v25, vcc
	v_cndmask_b32_e32 v26, 0, v26, vcc
	v_cndmask_b32_e32 v27, 0, v27, vcc
	v_cvt_pk_bf16_f32 v28, v12, v13
	v_cvt_pk_bf16_f32 v29, v14, v15
	v_cvt_pk_bf16_f32 v30, v16, v17
	v_cvt_pk_bf16_f32 v31, v18, v19
	v_cvt_pk_bf16_f32 v32, v20, v21
	v_cvt_pk_bf16_f32 v33, v22, v23
	v_cvt_pk_bf16_f32 v34, v24, v25
	v_cvt_pk_bf16_f32 v35, v26, v27
	global_store_dwordx4 v6, v[28:31], s[6:7] offset:0
	global_store_dwordx4 v6, v[32:35], s[6:7] offset:16
	v_subrev_u32_e32 v11, 1, v9
	v_cmp_le_i32_e32 vcc, 0, v11
	v_max_i32_e32 v11, 0, v11
	v_lshl_add_u32 v11, v11, 10, v10
	ds_read_b128 v[12:15], v11 offset:0
	ds_read_b128 v[16:19], v11 offset:16
	ds_read_b128 v[20:23], v11 offset:32
	ds_read_b128 v[24:27], v11 offset:48
	s_waitcnt lgkmcnt(0)
	v_cndmask_b32_e32 v12, 0, v12, vcc
	v_cndmask_b32_e32 v13, 0, v13, vcc
	v_cndmask_b32_e32 v14, 0, v14, vcc
	v_cndmask_b32_e32 v15, 0, v15, vcc
	v_cndmask_b32_e32 v16, 0, v16, vcc
	v_cndmask_b32_e32 v17, 0, v17, vcc
	v_cndmask_b32_e32 v18, 0, v18, vcc
	v_cndmask_b32_e32 v19, 0, v19, vcc
	v_cndmask_b32_e32 v20, 0, v20, vcc
	v_cndmask_b32_e32 v21, 0, v21, vcc
	v_cndmask_b32_e32 v22, 0, v22, vcc
	v_cndmask_b32_e32 v23, 0, v23, vcc
	v_cndmask_b32_e32 v24, 0, v24, vcc
	v_cndmask_b32_e32 v25, 0, v25, vcc
	v_cndmask_b32_e32 v26, 0, v26, vcc
	v_cndmask_b32_e32 v27, 0, v27, vcc
	v_cvt_pk_bf16_f32 v28, v12, v13
	v_cvt_pk_bf16_f32 v29, v14, v15
	v_cvt_pk_bf16_f32 v30, v16, v17
	v_cvt_pk_bf16_f32 v31, v18, v19
	v_cvt_pk_bf16_f32 v32, v20, v21
	v_cvt_pk_bf16_f32 v33, v22, v23
	v_cvt_pk_bf16_f32 v34, v24, v25
	v_cvt_pk_bf16_f32 v35, v26, v27
	global_store_dwordx4 v6, v[28:31], s[6:7] offset:32
	global_store_dwordx4 v6, v[32:35], s[6:7] offset:48
	v_subrev_u32_e32 v11, 2, v9
	v_cmp_le_i32_e32 vcc, 0, v11
	v_max_i32_e32 v11, 0, v11
	v_lshl_add_u32 v11, v11, 10, v10
	ds_read_b128 v[12:15], v11 offset:0
	ds_read_b128 v[16:19], v11 offset:16
	ds_read_b128 v[20:23], v11 offset:32
	ds_read_b128 v[24:27], v11 offset:48
	s_waitcnt lgkmcnt(0)
	v_cndmask_b32_e32 v12, 0, v12, vcc
	v_cndmask_b32_e32 v13, 0, v13, vcc
	v_cndmask_b32_e32 v14, 0, v14, vcc
	v_cndmask_b32_e32 v15, 0, v15, vcc
	v_cndmask_b32_e32 v16, 0, v16, vcc
	v_cndmask_b32_e32 v17, 0, v17, vcc
	v_cndmask_b32_e32 v18, 0, v18, vcc
	v_cndmask_b32_e32 v19, 0, v19, vcc
	v_cndmask_b32_e32 v20, 0, v20, vcc
	v_cndmask_b32_e32 v21, 0, v21, vcc
	v_cndmask_b32_e32 v22, 0, v22, vcc
	v_cndmask_b32_e32 v23, 0, v23, vcc
	v_cndmask_b32_e32 v24, 0, v24, vcc
	v_cndmask_b32_e32 v25, 0, v25, vcc
	v_cndmask_b32_e32 v26, 0, v26, vcc
	v_cndmask_b32_e32 v27, 0, v27, vcc
	v_cvt_pk_bf16_f32 v28, v12, v13
	v_cvt_pk_bf16_f32 v29, v14, v15
	v_cvt_pk_bf16_f32 v30, v16, v17
	v_cvt_pk_bf16_f32 v31, v18, v19
	v_cvt_pk_bf16_f32 v32, v20, v21
	v_cvt_pk_bf16_f32 v33, v22, v23
	v_cvt_pk_bf16_f32 v34, v24, v25
	v_cvt_pk_bf16_f32 v35, v26, v27
	global_store_dwordx4 v6, v[28:31], s[6:7] offset:64
	global_store_dwordx4 v6, v[32:35], s[6:7] offset:80
	v_subrev_u32_e32 v11, 3, v9
	v_cmp_le_i32_e32 vcc, 0, v11
	v_max_i32_e32 v11, 0, v11
	v_lshl_add_u32 v11, v11, 10, v10
	ds_read_b128 v[12:15], v11 offset:0
	ds_read_b128 v[16:19], v11 offset:16
	ds_read_b128 v[20:23], v11 offset:32
	ds_read_b128 v[24:27], v11 offset:48
	s_waitcnt lgkmcnt(0)
	v_cndmask_b32_e32 v12, 0, v12, vcc
	v_cndmask_b32_e32 v13, 0, v13, vcc
	v_cndmask_b32_e32 v14, 0, v14, vcc
	v_cndmask_b32_e32 v15, 0, v15, vcc
	v_cndmask_b32_e32 v16, 0, v16, vcc
	v_cndmask_b32_e32 v17, 0, v17, vcc
	v_cndmask_b32_e32 v18, 0, v18, vcc
	v_cndmask_b32_e32 v19, 0, v19, vcc
	v_cndmask_b32_e32 v20, 0, v20, vcc
	v_cndmask_b32_e32 v21, 0, v21, vcc
	v_cndmask_b32_e32 v22, 0, v22, vcc
	v_cndmask_b32_e32 v23, 0, v23, vcc
	v_cndmask_b32_e32 v24, 0, v24, vcc
	v_cndmask_b32_e32 v25, 0, v25, vcc
	v_cndmask_b32_e32 v26, 0, v26, vcc
	v_cndmask_b32_e32 v27, 0, v27, vcc
	v_cvt_pk_bf16_f32 v28, v12, v13
	v_cvt_pk_bf16_f32 v29, v14, v15
	v_cvt_pk_bf16_f32 v30, v16, v17
	v_cvt_pk_bf16_f32 v31, v18, v19
	v_cvt_pk_bf16_f32 v32, v20, v21
	v_cvt_pk_bf16_f32 v33, v22, v23
	v_cvt_pk_bf16_f32 v34, v24, v25
	v_cvt_pk_bf16_f32 v35, v26, v27
	global_store_dwordx4 v6, v[28:31], s[6:7] offset:96
	global_store_dwordx4 v6, v[32:35], s[6:7] offset:112
	v_subrev_u32_e32 v11, 4, v9
	v_cmp_le_i32_e32 vcc, 0, v11
	v_max_i32_e32 v11, 0, v11
	v_lshl_add_u32 v11, v11, 10, v10
	ds_read_b128 v[12:15], v11 offset:0
	ds_read_b128 v[16:19], v11 offset:16
	ds_read_b128 v[20:23], v11 offset:32
	ds_read_b128 v[24:27], v11 offset:48
	s_waitcnt lgkmcnt(0)
; __device__ __forceinline__ unsigned pk2(float lo, float hi) { typedef __bf16 bf16x2_t_ __attribute__((ext_vector_type(2))); f32x2 v = {lo, hi}; return __builtin_bit_cast(unsigned, __builtin_convertvector(v, bf16x2_t_)); }
; __device__ __forceinline__ f32x2 cmul(f32x2 a, f32x2 b) { return (f32x2){a.x * b.x - a.y * b.y, a.x * b.y + a.y * b.x}; }
; __global__ void __launch_bounds__(NTHR, 2) hymba_fwd(Params P) {
;     ...
;             bf16_t* w2 = W2 + (size_t)g * 256 * 384;
;             for (int idx = tid; idx < 256 * 192; idx += NTHR) { const int c = idx / 192, k = (idx % 192) * 2, t = c >> 4, p = c & 15; float v[2];
; #pragma unroll
;                 for (int e = 0; e < 2; ++e) { const int kk = k + e; float r;
;                     if (kk < 256) { const int s = kk >> 4, pp = kk & 15; r = (s <= t) ? KT[((t - s) * 16 + p) * 16 + pp] : 0.f; }
;                     else { const int n = (kk - 256) & 63; const f32x2 z = cmul(CCl[p * 64 + n], PW[(t + 1) * 64 + n]); r = (kk < 320) ? z.x : -z.y; }
;                     v[e] = r; }
;                 *(unsigned*)(w2 + (size_t)c * 384 + k) = pk2(v[0], v[1]); }
	v_cndmask_b32_e32 v12, 0, v12, vcc
	v_cndmask_b32_e32 v13, 0, v13, vcc
	v_cndmask_b32_e32 v14, 0, v14, vcc
	v_cndmask_b32_e32 v15, 0, v15, vcc
	v_cndmask_b32_e32 v16, 0, v16, vcc
	v_cndmask_b32_e32 v17, 0, v17, vcc
	v_cndmask_b32_e32 v18, 0, v18, vcc
	v_cndmask_b32_e32 v19, 0, v19, vcc
	v_cndmask_b32_e32 v20, 0, v20, vcc
	v_cndmask_b32_e32 v21, 0, v21, vcc
	v_cndmask_b32_e32 v22, 0, v22, vcc
	v_cndmask_b32_e32 v23, 0, v23, vcc
	v_cndmask_b32_e32 v24, 0, v24, vcc
	v_cndmask_b32_e32 v25, 0, v25, vcc
	v_cndmask_b32_e32 v26, 0, v26, vcc
	v_cndmask_b32_e32 v27, 0, v27, vcc
	v_cvt_pk_bf16_f32 v28, v12, v13
	v_cvt_pk_bf16_f32 v29, v14, v15
	v_cvt_pk_bf16_f32 v30, v16, v17
	v_cvt_pk_bf16_f32 v31, v18, v19
	v_cvt_pk_bf16_f32 v32, v20, v21
	v_cvt_pk_bf16_f32 v33, v22, v23
	v_cvt_pk_bf16_f32 v34, v24, v25
	v_cvt_pk_bf16_f32 v35, v26, v27
	global_store_dwordx4 v6, v[28:31], s[6:7] offset:128
	global_store_dwordx4 v6, v[32:35], s[6:7] offset:144
	v_subrev_u32_e32 v11, 5, v9
	v_cmp_le_i32_e32 vcc, 0, v11
	v_max_i32_e32 v11, 0, v11
	v_lshl_add_u32 v11, v11, 10, v10
	ds_read_b128 v[12:15], v11 offset:0
	ds_read_b128 v[16:19], v11 offset:16
	ds_read_b128 v[20:23], v11 offset:32
	ds_read_b128 v[24:27], v11 offset:48
	s_waitcnt lgkmcnt(0)
	v_cndmask_b32_e32 v12, 0, v12, vcc
	v_cndmask_b32_e32 v13, 0, v13, vcc
	v_cndmask_b32_e32 v14, 0, v14, vcc
	v_cndmask_b32_e32 v15, 0, v15, vcc
	v_cndmask_b32_e32 v16, 0, v16, vcc
	v_cndmask_b32_e32 v17, 0, v17, vcc
	v_cndmask_b32_e32 v18, 0, v18, vcc
	v_cndmask_b32_e32 v19, 0, v19, vcc
	v_cndmask_b32_e32 v20, 0, v20, vcc
	v_cndmask_b32_e32 v21, 0, v21, vcc
	v_cndmask_b32_e32 v22, 0, v22, vcc
	v_cndmask_b32_e32 v23, 0, v23, vcc
	v_cndmask_b32_e32 v24, 0, v24, vcc
	v_cndmask_b32_e32 v25, 0, v25, vcc
	v_cndmask_b32_e32 v26, 0, v26, vcc
	v_cndmask_b32_e32 v27, 0, v27, vcc
	v_cvt_pk_bf16_f32 v28, v12, v13
	v_cvt_pk_bf16_f32 v29, v14, v15
	v_cvt_pk_bf16_f32 v30, v16, v17
	v_cvt_pk_bf16_f32 v31, v18, v19
	v_cvt_pk_bf16_f32 v32, v20, v21
	v_cvt_pk_bf16_f32 v33, v22, v23
	v_cvt_pk_bf16_f32 v34, v24, v25
	v_cvt_pk_bf16_f32 v35, v26, v27
	global_store_dwordx4 v6, v[28:31], s[6:7] offset:160
	global_store_dwordx4 v6, v[32:35], s[6:7] offset:176
	v_subrev_u32_e32 v11, 6, v9
	v_cmp_le_i32_e32 vcc, 0, v11
	v_max_i32_e32 v11, 0, v11
	v_lshl_add_u32 v11, v11, 10, v10
	ds_read_b128 v[12:15], v11 offset:0
	ds_read_b128 v[16:19], v11 offset:16
	ds_read_b128 v[20:23], v11 offset:32
	ds_read_b128 v[24:27], v11 offset:48
	s_waitcnt lgkmcnt(0)
	v_cndmask_b32_e32 v12, 0, v12, vcc
	v_cndmask_b32_e32 v13, 0, v13, vcc
	v_cndmask_b32_e32 v14, 0, v14, vcc
	v_cndmask_b32_e32 v15, 0, v15, vcc
	v_cndmask_b32_e32 v16, 0, v16, vcc
	v_cndmask_b32_e32 v17, 0, v17, vcc
	v_cndmask_b32_e32 v18, 0, v18, vcc
	v_cndmask_b32_e32 v19, 0, v19, vcc
	v_cndmask_b32_e32 v20, 0, v20, vcc
	v_cndmask_b32_e32 v21, 0, v21, vcc
	v_cndmask_b32_e32 v22, 0, v22, vcc
	v_cndmask_b32_e32 v23, 0, v23, vcc
	v_cndmask_b32_e32 v24, 0, v24, vcc
	v_cndmask_b32_e32 v25, 0, v25, vcc
	v_cndmask_b32_e32 v26, 0, v26, vcc
	v_cndmask_b32_e32 v27, 0, v27, vcc
	v_cvt_pk_bf16_f32 v28, v12, v13
	v_cvt_pk_bf16_f32 v29, v14, v15
	v_cvt_pk_bf16_f32 v30, v16, v17
	v_cvt_pk_bf16_f32 v31, v18, v19
	v_cvt_pk_bf16_f32 v32, v20, v21
	v_cvt_pk_bf16_f32 v33, v22, v23
	v_cvt_pk_bf16_f32 v34, v24, v25
	v_cvt_pk_bf16_f32 v35, v26, v27
	global_store_dwordx4 v6, v[28:31], s[6:7] offset:192
	global_store_dwordx4 v6, v[32:35], s[6:7] offset:208
	v_subrev_u32_e32 v11, 7, v9
	v_cmp_le_i32_e32 vcc, 0, v11
	v_max_i32_e32 v11, 0, v11
	v_lshl_add_u32 v11, v11, 10, v10
	ds_read_b128 v[12:15], v11 offset:0
	ds_read_b128 v[16:19], v11 offset:16
	ds_read_b128 v[20:23], v11 offset:32
	ds_read_b128 v[24:27], v11 offset:48
	s_waitcnt lgkmcnt(0)
	v_cndmask_b32_e32 v12, 0, v12, vcc
	v_cndmask_b32_e32 v13, 0, v13, vcc
	v_cndmask_b32_e32 v14, 0, v14, vcc
	v_cndmask_b32_e32 v15, 0, v15, vcc
	v_cndmask_b32_e32 v16, 0, v16, vcc
	v_cndmask_b32_e32 v17, 0, v17, vcc
	v_cndmask_b32_e32 v18, 0, v18, vcc
	v_cndmask_b32_e32 v19, 0, v19, vcc
	v_cndmask_b32_e32 v20, 0, v20, vcc
	v_cndmask_b32_e32 v21, 0, v21, vcc
	v_cndmask_b32_e32 v22, 0, v22, vcc
	v_cndmask_b32_e32 v23, 0, v23, vcc
	v_cndmask_b32_e32 v24, 0, v24, vcc
	v_cndmask_b32_e32 v25, 0, v25, vcc
	v_cndmask_b32_e32 v26, 0, v26, vcc
	v_cndmask_b32_e32 v27, 0, v27, vcc
	v_cvt_pk_bf16_f32 v28, v12, v13
	v_cvt_pk_bf16_f32 v29, v14, v15
	v_cvt_pk_bf16_f32 v30, v16, v17
	v_cvt_pk_bf16_f32 v31, v18, v19
	v_cvt_pk_bf16_f32 v32, v20, v21
	v_cvt_pk_bf16_f32 v33, v22, v23
	v_cvt_pk_bf16_f32 v34, v24, v25
	v_cvt_pk_bf16_f32 v35, v26, v27
	global_store_dwordx4 v6, v[28:31], s[6:7] offset:224
	global_store_dwordx4 v6, v[32:35], s[6:7] offset:240
	v_lshlrev_b32_e32 v11, 9, v5
	v_lshl_add_u32 v11, v3, 8, v11
	v_add_u32_e32 v11, 0x4200, v11
	v_add_u32_e32 v12, 1, v4
	v_lshlrev_b32_e32 v12, 9, v12
	v_lshl_add_u32 v12, v3, 8, v12
	v_mul_u32_u24_e32 v13, 0x300, v2
	v_lshl_add_u32 v13, v3, 6, v13
	ds_read_b128 v[84:87], v11 offset:0
	ds_read_b128 v[88:91], v11 offset:16
	ds_read_b128 v[92:95], v11 offset:32
	ds_read_b128 v[96:99], v11 offset:48
	ds_read_b128 v[100:103], v12 offset:0
	ds_read_b128 v[104:107], v12 offset:16
	ds_read_b128 v[108:111], v12 offset:32
	ds_read_b128 v[112:115], v12 offset:48
	s_waitcnt lgkmcnt(0)
; __device__ __forceinline__ unsigned pk2(float lo, float hi) { typedef __bf16 bf16x2_t_ __attribute__((ext_vector_type(2))); f32x2 v = {lo, hi}; return __builtin_bit_cast(unsigned, __builtin_convertvector(v, bf16x2_t_)); }
; __device__ __forceinline__ f32x2 cmul(f32x2 a, f32x2 b) { return (f32x2){a.x * b.x - a.y * b.y, a.x * b.y + a.y * b.x}; }
; __global__ void __launch_bounds__(NTHR, 2) hymba_fwd(Params P) {
;     ...
;             bf16_t* w2 = W2 + (size_t)g * 256 * 384;
;             for (int idx = tid; idx < 256 * 192; idx += NTHR) { const int c = idx / 192, k = (idx % 192) * 2, t = c >> 4, p = c & 15; float v[2];
; #pragma unroll
;                 for (int e = 0; e < 2; ++e) { const int kk = k + e; float r;
;                     if (kk < 256) { const int s = kk >> 4, pp = kk & 15; r = (s <= t) ? KT[((t - s) * 16 + p) * 16 + pp] : 0.f; }
;                     else { const int n = (kk - 256) & 63; const f32x2 z = cmul(CCl[p * 64 + n], PW[(t + 1) * 64 + n]); r = (kk < 320) ? z.x : -z.y; }
;                     v[e] = r; }
;                 *(unsigned*)(w2 + (size_t)c * 384 + k) = pk2(v[0], v[1]); }
	v_mul_f32_e32 v116, v84, v100
	v_mul_f32_e32 v117, v85, v101
	v_mul_f32_e32 v118, v84, v101
	v_mul_f32_e32 v119, v85, v100
	v_sub_f32_e32 v120, v116, v117
	v_add_f32_e32 v118, v118, v119
	v_mul_f32_e32 v128, -1.0, v118
	v_mul_f32_e32 v116, v86, v102
	v_mul_f32_e32 v117, v87, v103
	v_mul_f32_e32 v118, v86, v103
	v_mul_f32_e32 v119, v87, v102
	v_sub_f32_e32 v121, v116, v117
	v_add_f32_e32 v118, v118, v119
	v_mul_f32_e32 v129, -1.0, v118
	v_mul_f32_e32 v116, v88, v104
	v_mul_f32_e32 v117, v89, v105
	v_mul_f32_e32 v118, v88, v105
	v_mul_f32_e32 v119, v89, v104
	v_sub_f32_e32 v122, v116, v117
	v_add_f32_e32 v118, v118, v119
	v_mul_f32_e32 v130, -1.0, v118
	v_mul_f32_e32 v116, v90, v106
	v_mul_f32_e32 v117, v91, v107
	v_mul_f32_e32 v118, v90, v107
	v_mul_f32_e32 v119, v91, v106
	v_sub_f32_e32 v123, v116, v117
	v_add_f32_e32 v118, v118, v119
	v_mul_f32_e32 v131, -1.0, v118
	v_mul_f32_e32 v116, v92, v108
	v_mul_f32_e32 v117, v93, v109
	v_mul_f32_e32 v118, v92, v109
	v_mul_f32_e32 v119, v93, v108
	v_sub_f32_e32 v124, v116, v117
	v_add_f32_e32 v118, v118, v119
	v_mul_f32_e32 v132, -1.0, v118
	v_mul_f32_e32 v116, v94, v110
	v_mul_f32_e32 v117, v95, v111
	v_mul_f32_e32 v118, v94, v111
	v_mul_f32_e32 v119, v95, v110
	v_sub_f32_e32 v125, v116, v117
	v_add_f32_e32 v118, v118, v119
	v_mul_f32_e32 v133, -1.0, v118
	v_mul_f32_e32 v116, v96, v112
	v_mul_f32_e32 v117, v97, v113
	v_mul_f32_e32 v118, v96, v113
	v_mul_f32_e32 v119, v97, v112
	v_sub_f32_e32 v126, v116, v117
	v_add_f32_e32 v118, v118, v119
	v_mul_f32_e32 v134, -1.0, v118
	v_mul_f32_e32 v116, v98, v114
	v_mul_f32_e32 v117, v99, v115
	v_mul_f32_e32 v118, v98, v115
	v_mul_f32_e32 v119, v99, v114
	v_sub_f32_e32 v127, v116, v117
	v_add_f32_e32 v118, v118, v119
	v_mul_f32_e32 v135, -1.0, v118
	v_cvt_pk_bf16_f32 v136, v120, v121
	v_cvt_pk_bf16_f32 v140, v128, v129
	v_cvt_pk_bf16_f32 v137, v122, v123
	v_cvt_pk_bf16_f32 v141, v130, v131
	v_cvt_pk_bf16_f32 v138, v124, v125
	v_cvt_pk_bf16_f32 v142, v132, v133
	v_cvt_pk_bf16_f32 v139, v126, v127
	v_cvt_pk_bf16_f32 v143, v134, v135
	global_store_dwordx4 v13, v[136:139], s[6:7] offset:512
	global_store_dwordx4 v13, v[140:143], s[6:7] offset:640
	ds_read_b128 v[84:87], v11 offset:64
	ds_read_b128 v[88:91], v11 offset:80
	ds_read_b128 v[92:95], v11 offset:96
	ds_read_b128 v[96:99], v11 offset:112
	ds_read_b128 v[100:103], v12 offset:64
	ds_read_b128 v[104:107], v12 offset:80
	ds_read_b128 v[108:111], v12 offset:96
	ds_read_b128 v[112:115], v12 offset:112
	s_waitcnt lgkmcnt(0)
	v_mul_f32_e32 v116, v84, v100
	v_mul_f32_e32 v117, v85, v101
	v_mul_f32_e32 v118, v84, v101
	v_mul_f32_e32 v119, v85, v100
	v_sub_f32_e32 v120, v116, v117
	v_add_f32_e32 v118, v118, v119
	v_mul_f32_e32 v128, -1.0, v118
	v_mul_f32_e32 v116, v86, v102
	v_mul_f32_e32 v117, v87, v103
	v_mul_f32_e32 v118, v86, v103
	v_mul_f32_e32 v119, v87, v102
	v_sub_f32_e32 v121, v116, v117
	v_add_f32_e32 v118, v118, v119
	v_mul_f32_e32 v129, -1.0, v118
	v_mul_f32_e32 v116, v88, v104
	v_mul_f32_e32 v117, v89, v105
	v_mul_f32_e32 v118, v88, v105
	v_mul_f32_e32 v119, v89, v104
	v_sub_f32_e32 v122, v116, v117
	v_add_f32_e32 v118, v118, v119
	v_mul_f32_e32 v130, -1.0, v118
	v_mul_f32_e32 v116, v90, v106
	v_mul_f32_e32 v117, v91, v107
	v_mul_f32_e32 v118, v90, v107
	v_mul_f32_e32 v119, v91, v106
	v_sub_f32_e32 v123, v116, v117
	v_add_f32_e32 v118, v118, v119
	v_mul_f32_e32 v131, -1.0, v118
	v_mul_f32_e32 v116, v92, v108
	v_mul_f32_e32 v117, v93, v109
	v_mul_f32_e32 v118, v92, v109
	v_mul_f32_e32 v119, v93, v108
	v_sub_f32_e32 v124, v116, v117
	v_add_f32_e32 v118, v118, v119
	v_mul_f32_e32 v132, -1.0, v118
	v_mul_f32_e32 v116, v94, v110
	v_mul_f32_e32 v117, v95, v111
	v_mul_f32_e32 v118, v94, v111
	v_mul_f32_e32 v119, v95, v110
	v_sub_f32_e32 v125, v116, v117
	v_add_f32_e32 v118, v118, v119
	v_mul_f32_e32 v133, -1.0, v118
	v_mul_f32_e32 v116, v96, v112
	v_mul_f32_e32 v117, v97, v113
	v_mul_f32_e32 v118, v96, v113
	v_mul_f32_e32 v119, v97, v112
	v_sub_f32_e32 v126, v116, v117
	v_add_f32_e32 v118, v118, v119
	v_mul_f32_e32 v134, -1.0, v118
	v_mul_f32_e32 v116, v98, v114
	v_mul_f32_e32 v117, v99, v115
	v_mul_f32_e32 v118, v98, v115
	v_mul_f32_e32 v119, v99, v114
	v_sub_f32_e32 v127, v116, v117
	v_add_f32_e32 v118, v118, v119
	v_mul_f32_e32 v135, -1.0, v118
	v_cvt_pk_bf16_f32 v136, v120, v121
	v_cvt_pk_bf16_f32 v140, v128, v129
	v_cvt_pk_bf16_f32 v137, v122, v123
	v_cvt_pk_bf16_f32 v141, v130, v131
	v_cvt_pk_bf16_f32 v138, v124, v125
	v_cvt_pk_bf16_f32 v142, v132, v133
	v_cvt_pk_bf16_f32 v139, v126, v127
	v_cvt_pk_bf16_f32 v143, v134, v135
	global_store_dwordx4 v13, v[136:139], s[6:7] offset:528
	global_store_dwordx4 v13, v[140:143], s[6:7] offset:656
	ds_read_b128 v[84:87], v11 offset:128
	ds_read_b128 v[88:91], v11 offset:144
	ds_read_b128 v[92:95], v11 offset:160
	ds_read_b128 v[96:99], v11 offset:176
	ds_read_b128 v[100:103], v12 offset:128
	ds_read_b128 v[104:107], v12 offset:144
	ds_read_b128 v[108:111], v12 offset:160
	ds_read_b128 v[112:115], v12 offset:176
	s_waitcnt lgkmcnt(0)
; __device__ __forceinline__ unsigned pk2(float lo, float hi) { typedef __bf16 bf16x2_t_ __attribute__((ext_vector_type(2))); f32x2 v = {lo, hi}; return __builtin_bit_cast(unsigned, __builtin_convertvector(v, bf16x2_t_)); }
; __device__ __forceinline__ f32x2 cmul(f32x2 a, f32x2 b) { return (f32x2){a.x * b.x - a.y * b.y, a.x * b.y + a.y * b.x}; }
; __global__ void __launch_bounds__(NTHR, 2) hymba_fwd(Params P) {
;     ...
;             bf16_t* w2 = W2 + (size_t)g * 256 * 384;
;             for (int idx = tid; idx < 256 * 192; idx += NTHR) { const int c = idx / 192, k = (idx % 192) * 2, t = c >> 4, p = c & 15; float v[2];
; #pragma unroll
;                 for (int e = 0; e < 2; ++e) { const int kk = k + e; float r;
;                     if (kk < 256) { const int s = kk >> 4, pp = kk & 15; r = (s <= t) ? KT[((t - s) * 16 + p) * 16 + pp] : 0.f; }
;                     else { const int n = (kk - 256) & 63; const f32x2 z = cmul(CCl[p * 64 + n], PW[(t + 1) * 64 + n]); r = (kk < 320) ? z.x : -z.y; }
;                     v[e] = r; }
;                 *(unsigned*)(w2 + (size_t)c * 384 + k) = pk2(v[0], v[1]); }
;             bf16_t* w1 = W1 + (size_t)g * 256 * 256;
;             for (int idx = tid; idx < 256 * 128; idx += NTHR) { const int np = idx >> 7, k = (idx & 127) * 2; float v[2];
; #pragma unroll
;                 for (int e = 0; e < 2; ++e) { const int kk = k + e, s = kk >> 4, pp = kk & 15; float r = 0.f;
;                     if (np < 128) { const int n = np & 63; const f32x2 z = cmul(PW[(15 - s) * 64 + n], BBl[n * 16 + pp]); r = (np < 64) ? z.x : z.y; }
;                     v[e] = r; }
;                 *(unsigned*)(w1 + (size_t)np * 256 + k) = pk2(v[0], v[1]); }
	v_mul_f32_e32 v116, v84, v100
	v_mul_f32_e32 v117, v85, v101
	v_mul_f32_e32 v118, v84, v101
	v_mul_f32_e32 v119, v85, v100
	v_sub_f32_e32 v120, v116, v117
	v_add_f32_e32 v118, v118, v119
	v_mul_f32_e32 v128, -1.0, v118
	v_mul_f32_e32 v116, v86, v102
	v_mul_f32_e32 v117, v87, v103
	v_mul_f32_e32 v118, v86, v103
	v_mul_f32_e32 v119, v87, v102
	v_sub_f32_e32 v121, v116, v117
	v_add_f32_e32 v118, v118, v119
	v_mul_f32_e32 v129, -1.0, v118
	v_mul_f32_e32 v116, v88, v104
	v_mul_f32_e32 v117, v89, v105
	v_mul_f32_e32 v118, v88, v105
	v_mul_f32_e32 v119, v89, v104
	v_sub_f32_e32 v122, v116, v117
	v_add_f32_e32 v118, v118, v119
	v_mul_f32_e32 v130, -1.0, v118
	v_mul_f32_e32 v116, v90, v106
	v_mul_f32_e32 v117, v91, v107
	v_mul_f32_e32 v118, v90, v107
	v_mul_f32_e32 v119, v91, v106
	v_sub_f32_e32 v123, v116, v117
	v_add_f32_e32 v118, v118, v119
	v_mul_f32_e32 v131, -1.0, v118
	v_mul_f32_e32 v116, v92, v108
	v_mul_f32_e32 v117, v93, v109
	v_mul_f32_e32 v118, v92, v109
	v_mul_f32_e32 v119, v93, v108
	v_sub_f32_e32 v124, v116, v117
	v_add_f32_e32 v118, v118, v119
	v_mul_f32_e32 v132, -1.0, v118
	v_mul_f32_e32 v116, v94, v110
	v_mul_f32_e32 v117, v95, v111
	v_mul_f32_e32 v118, v94, v111
	v_mul_f32_e32 v119, v95, v110
	v_sub_f32_e32 v125, v116, v117
	v_add_f32_e32 v118, v118, v119
	v_mul_f32_e32 v133, -1.0, v118
	v_mul_f32_e32 v116, v96, v112
	v_mul_f32_e32 v117, v97, v113
	v_mul_f32_e32 v118, v96, v113
	v_mul_f32_e32 v119, v97, v112
	v_sub_f32_e32 v126, v116, v117
	v_add_f32_e32 v118, v118, v119
	v_mul_f32_e32 v134, -1.0, v118
	v_mul_f32_e32 v116, v98, v114
	v_mul_f32_e32 v117, v99, v115
	v_mul_f32_e32 v118, v98, v115
	v_mul_f32_e32 v119, v99, v114
	v_sub_f32_e32 v127, v116, v117
	v_add_f32_e32 v118, v118, v119
	v_mul_f32_e32 v135, -1.0, v118
	v_cvt_pk_bf16_f32 v136, v120, v121
	v_cvt_pk_bf16_f32 v140, v128, v129
	v_cvt_pk_bf16_f32 v137, v122, v123
	v_cvt_pk_bf16_f32 v141, v130, v131
	v_cvt_pk_bf16_f32 v138, v124, v125
	v_cvt_pk_bf16_f32 v142, v132, v133
	v_cvt_pk_bf16_f32 v139, v126, v127
	v_cvt_pk_bf16_f32 v143, v134, v135
	global_store_dwordx4 v13, v[136:139], s[6:7] offset:544
	global_store_dwordx4 v13, v[140:143], s[6:7] offset:672
	ds_read_b128 v[84:87], v11 offset:192
	ds_read_b128 v[88:91], v11 offset:208
	ds_read_b128 v[92:95], v11 offset:224
	ds_read_b128 v[96:99], v11 offset:240
	ds_read_b128 v[100:103], v12 offset:192
	ds_read_b128 v[104:107], v12 offset:208
	ds_read_b128 v[108:111], v12 offset:224
	ds_read_b128 v[112:115], v12 offset:240
	s_waitcnt lgkmcnt(0)
	v_mul_f32_e32 v116, v84, v100
	v_mul_f32_e32 v117, v85, v101
	v_mul_f32_e32 v118, v84, v101
	v_mul_f32_e32 v119, v85, v100
	v_sub_f32_e32 v120, v116, v117
	v_add_f32_e32 v118, v118, v119
	v_mul_f32_e32 v128, -1.0, v118
	v_mul_f32_e32 v116, v86, v102
	v_mul_f32_e32 v117, v87, v103
	v_mul_f32_e32 v118, v86, v103
	v_mul_f32_e32 v119, v87, v102
	v_sub_f32_e32 v121, v116, v117
	v_add_f32_e32 v118, v118, v119
	v_mul_f32_e32 v129, -1.0, v118
	v_mul_f32_e32 v116, v88, v104
	v_mul_f32_e32 v117, v89, v105
	v_mul_f32_e32 v118, v88, v105
	v_mul_f32_e32 v119, v89, v104
	v_sub_f32_e32 v122, v116, v117
	v_add_f32_e32 v118, v118, v119
	v_mul_f32_e32 v130, -1.0, v118
	v_mul_f32_e32 v116, v90, v106
	v_mul_f32_e32 v117, v91, v107
	v_mul_f32_e32 v118, v90, v107
	v_mul_f32_e32 v119, v91, v106
	v_sub_f32_e32 v123, v116, v117
	v_add_f32_e32 v118, v118, v119
	v_mul_f32_e32 v131, -1.0, v118
	v_mul_f32_e32 v116, v92, v108
	v_mul_f32_e32 v117, v93, v109
	v_mul_f32_e32 v118, v92, v109
	v_mul_f32_e32 v119, v93, v108
	v_sub_f32_e32 v124, v116, v117
	v_add_f32_e32 v118, v118, v119
	v_mul_f32_e32 v132, -1.0, v118
	v_mul_f32_e32 v116, v94, v110
	v_mul_f32_e32 v117, v95, v111
	v_mul_f32_e32 v118, v94, v111
	v_mul_f32_e32 v119, v95, v110
	v_sub_f32_e32 v125, v116, v117
	v_add_f32_e32 v118, v118, v119
	v_mul_f32_e32 v133, -1.0, v118
	v_mul_f32_e32 v116, v96, v112
	v_mul_f32_e32 v117, v97, v113
	v_mul_f32_e32 v118, v96, v113
	v_mul_f32_e32 v119, v97, v112
	v_sub_f32_e32 v126, v116, v117
	v_add_f32_e32 v118, v118, v119
	v_mul_f32_e32 v134, -1.0, v118
	v_mul_f32_e32 v116, v98, v114
	v_mul_f32_e32 v117, v99, v115
	v_mul_f32_e32 v118, v98, v115
	v_mul_f32_e32 v119, v99, v114
	v_sub_f32_e32 v127, v116, v117
	v_add_f32_e32 v118, v118, v119
	v_mul_f32_e32 v135, -1.0, v118
	v_cvt_pk_bf16_f32 v136, v120, v121
	v_cvt_pk_bf16_f32 v140, v128, v129
	v_cvt_pk_bf16_f32 v137, v122, v123
	v_cvt_pk_bf16_f32 v141, v130, v131
	v_cvt_pk_bf16_f32 v138, v124, v125
	v_cvt_pk_bf16_f32 v142, v132, v133
	v_cvt_pk_bf16_f32 v139, v126, v127
	v_cvt_pk_bf16_f32 v143, v134, v135
	global_store_dwordx4 v13, v[136:139], s[6:7] offset:560
	global_store_dwordx4 v13, v[140:143], s[6:7] offset:688
	v_and_b32_e32 v14, 63, v2
	v_lshrrev_b32_e32 v15, 6, v2
	v_lshlrev_b32_e32 v16, 7, v14
	v_add_u32_e32 v16, 0x2200, v16
	ds_read_b128 v[84:87], v16 offset:0
	ds_read_b128 v[88:91], v16 offset:16
	ds_read_b128 v[92:95], v16 offset:32
	ds_read_b128 v[96:99], v16 offset:48
	ds_read_b128 v[100:103], v16 offset:64
	ds_read_b128 v[104:107], v16 offset:80
	ds_read_b128 v[108:111], v16 offset:96
	ds_read_b128 v[112:115], v16 offset:112
	v_sub_u32_e32 v17, 1, v3
	v_lshlrev_b32_e32 v17, 12, v17
	v_lshl_add_u32 v17, v14, 3, v17
	ds_read_b64 v[116:117], v17 offset:3584
	ds_read_b64 v[118:119], v17 offset:3072
	ds_read_b64 v[120:121], v17 offset:2560
	ds_read_b64 v[122:123], v17 offset:2048
	ds_read_b64 v[124:125], v17 offset:1536
	ds_read_b64 v[126:127], v17 offset:1024
	ds_read_b64 v[128:129], v17 offset:512
	ds_read_b64 v[130:131], v17 offset:0
	v_lshlrev_b32_e32 v18, 9, v2
	v_lshl_add_u32 v18, v3, 8, v18
	v_cmp_eq_u32_e32 vcc, 1, v15
	v_cmp_gt_u32_e64 s[16:17], 2, v15
	s_waitcnt lgkmcnt(0)
; __device__ __forceinline__ unsigned pk2(float lo, float hi) { typedef __bf16 bf16x2_t_ __attribute__((ext_vector_type(2))); f32x2 v = {lo, hi}; return __builtin_bit_cast(unsigned, __builtin_convertvector(v, bf16x2_t_)); }
; __device__ __forceinline__ f32x2 cmul(f32x2 a, f32x2 b) { return (f32x2){a.x * b.x - a.y * b.y, a.x * b.y + a.y * b.x}; }
; __global__ void __launch_bounds__(NTHR, 2) hymba_fwd(Params P) {
;     ...
;             bf16_t* w1 = W1 + (size_t)g * 256 * 256;
;             for (int idx = tid; idx < 256 * 128; idx += NTHR) { const int np = idx >> 7, k = (idx & 127) * 2; float v[2];
; #pragma unroll
;                 for (int e = 0; e < 2; ++e) { const int kk = k + e, s = kk >> 4, pp = kk & 15; float r = 0.f;
;                     if (np < 128) { const int n = np & 63; const f32x2 z = cmul(PW[(15 - s) * 64 + n], BBl[n * 16 + pp]); r = (np < 64) ? z.x : z.y; }
;                     v[e] = r; }
;                 *(unsigned*)(w1 + (size_t)np * 256 + k) = pk2(v[0], v[1]); }
	v_mul_f32_e32 v19, -1.0, v85
	v_cndmask_b32_e32 v150, v84, v85, vcc
	v_cndmask_b32_e32 v151, v19, v84, vcc
	v_mul_f32_e32 v19, -1.0, v87
	v_cndmask_b32_e32 v152, v86, v87, vcc
	v_cndmask_b32_e32 v153, v19, v86, vcc
	v_mul_f32_e32 v19, -1.0, v89
	v_cndmask_b32_e32 v154, v88, v89, vcc
	v_cndmask_b32_e32 v155, v19, v88, vcc
	v_mul_f32_e32 v19, -1.0, v91
	v_cndmask_b32_e32 v156, v90, v91, vcc
	v_cndmask_b32_e32 v157, v19, v90, vcc
	v_mul_f32_e32 v19, -1.0, v93
	v_cndmask_b32_e32 v158, v92, v93, vcc
	v_cndmask_b32_e32 v159, v19, v92, vcc
	v_mul_f32_e32 v19, -1.0, v95
	v_cndmask_b32_e32 v160, v94, v95, vcc
	v_cndmask_b32_e32 v161, v19, v94, vcc
	v_mul_f32_e32 v19, -1.0, v97
	v_cndmask_b32_e32 v162, v96, v97, vcc
	v_cndmask_b32_e32 v163, v19, v96, vcc
	v_mul_f32_e32 v19, -1.0, v99
	v_cndmask_b32_e32 v164, v98, v99, vcc
	v_cndmask_b32_e32 v165, v19, v98, vcc
	v_mul_f32_e32 v19, -1.0, v101
	v_cndmask_b32_e32 v166, v100, v101, vcc
	v_cndmask_b32_e32 v167, v19, v100, vcc
	v_mul_f32_e32 v19, -1.0, v103
	v_cndmask_b32_e32 v168, v102, v103, vcc
	v_cndmask_b32_e32 v169, v19, v102, vcc
	v_mul_f32_e32 v19, -1.0, v105
	v_cndmask_b32_e32 v170, v104, v105, vcc
	v_cndmask_b32_e32 v171, v19, v104, vcc
	v_mul_f32_e32 v19, -1.0, v107
	v_cndmask_b32_e32 v172, v106, v107, vcc
	v_cndmask_b32_e32 v173, v19, v106, vcc
	v_mul_f32_e32 v19, -1.0, v109
	v_cndmask_b32_e32 v174, v108, v109, vcc
	v_cndmask_b32_e32 v175, v19, v108, vcc
	v_mul_f32_e32 v19, -1.0, v111
	v_cndmask_b32_e32 v176, v110, v111, vcc
	v_cndmask_b32_e32 v177, v19, v110, vcc
	v_mul_f32_e32 v19, -1.0, v113
	v_cndmask_b32_e32 v178, v112, v113, vcc
	v_cndmask_b32_e32 v179, v19, v112, vcc
	v_mul_f32_e32 v19, -1.0, v115
	v_cndmask_b32_e32 v180, v114, v115, vcc
	v_cndmask_b32_e32 v181, v19, v114, vcc
	v_cndmask_b32_e64 v19, 0, 1.0, s[16:17]
	v_mul_f32_e32 v116, v116, v19
	v_mul_f32_e32 v117, v117, v19
	v_mul_f32_e32 v118, v118, v19
	v_mul_f32_e32 v119, v119, v19
	v_mul_f32_e32 v120, v120, v19
	v_mul_f32_e32 v121, v121, v19
	v_mul_f32_e32 v122, v122, v19
	v_mul_f32_e32 v123, v123, v19
	v_mul_f32_e32 v124, v124, v19
	v_mul_f32_e32 v125, v125, v19
	v_mul_f32_e32 v126, v126, v19
	v_mul_f32_e32 v127, v127, v19
	v_mul_f32_e32 v128, v128, v19
	v_mul_f32_e32 v129, v129, v19
	v_mul_f32_e32 v130, v130, v19
	v_mul_f32_e32 v131, v131, v19
	v_mul_f32_e32 v20, v116, v150
	v_mul_f32_e32 v21, v117, v151
	v_add_f32_e32 v22, v20, v21
	v_mul_f32_e32 v20, v116, v152
	v_mul_f32_e32 v21, v117, v153
	v_add_f32_e32 v23, v20, v21
	v_mul_f32_e32 v20, v116, v154
	v_mul_f32_e32 v21, v117, v155
	v_add_f32_e32 v24, v20, v21
	v_mul_f32_e32 v20, v116, v156
	v_mul_f32_e32 v21, v117, v157
	v_add_f32_e32 v25, v20, v21
	v_mul_f32_e32 v20, v116, v158
	v_mul_f32_e32 v21, v117, v159
	v_add_f32_e32 v26, v20, v21
	v_mul_f32_e32 v20, v116, v160
	v_mul_f32_e32 v21, v117, v161
	v_add_f32_e32 v27, v20, v21
	v_mul_f32_e32 v20, v116, v162
	v_mul_f32_e32 v21, v117, v163
	v_add_f32_e32 v28, v20, v21
	v_mul_f32_e32 v20, v116, v164
	v_mul_f32_e32 v21, v117, v165
	v_add_f32_e32 v29, v20, v21
	v_mul_f32_e32 v20, v116, v166
	v_mul_f32_e32 v21, v117, v167
	v_add_f32_e32 v30, v20, v21
	v_mul_f32_e32 v20, v116, v168
	v_mul_f32_e32 v21, v117, v169
	v_add_f32_e32 v31, v20, v21
	v_mul_f32_e32 v20, v116, v170
	v_mul_f32_e32 v21, v117, v171
	v_add_f32_e32 v32, v20, v21
	v_mul_f32_e32 v20, v116, v172
	v_mul_f32_e32 v21, v117, v173
	v_add_f32_e32 v33, v20, v21
	v_mul_f32_e32 v20, v116, v174
	v_mul_f32_e32 v21, v117, v175
	v_add_f32_e32 v34, v20, v21
	v_mul_f32_e32 v20, v116, v176
	v_mul_f32_e32 v21, v117, v177
	v_add_f32_e32 v35, v20, v21
	v_mul_f32_e32 v20, v116, v178
	v_mul_f32_e32 v21, v117, v179
	v_add_f32_e32 v36, v20, v21
	v_mul_f32_e32 v20, v116, v180
	v_mul_f32_e32 v21, v117, v181
	v_add_f32_e32 v37, v20, v21
	v_cvt_pk_bf16_f32 v132, v22, v23
	v_cvt_pk_bf16_f32 v133, v24, v25
	v_cvt_pk_bf16_f32 v134, v26, v27
	v_cvt_pk_bf16_f32 v135, v28, v29
	v_cvt_pk_bf16_f32 v136, v30, v31
	v_cvt_pk_bf16_f32 v137, v32, v33
	v_cvt_pk_bf16_f32 v138, v34, v35
	v_cvt_pk_bf16_f32 v139, v36, v37
	global_store_dwordx4 v18, v[132:135], s[14:15] offset:0
	global_store_dwordx4 v18, v[136:139], s[14:15] offset:16
	v_mul_f32_e32 v20, v118, v150
	v_mul_f32_e32 v21, v119, v151
	v_add_f32_e32 v22, v20, v21
	v_mul_f32_e32 v20, v118, v152
	v_mul_f32_e32 v21, v119, v153
	v_add_f32_e32 v23, v20, v21
	v_mul_f32_e32 v20, v118, v154
	v_mul_f32_e32 v21, v119, v155
	v_add_f32_e32 v24, v20, v21
	v_mul_f32_e32 v20, v118, v156
	v_mul_f32_e32 v21, v119, v157
	v_add_f32_e32 v25, v20, v21
	v_mul_f32_e32 v20, v118, v158
	v_mul_f32_e32 v21, v119, v159
	v_add_f32_e32 v26, v20, v21
	v_mul_f32_e32 v20, v118, v160
	v_mul_f32_e32 v21, v119, v161
	v_add_f32_e32 v27, v20, v21
	v_mul_f32_e32 v20, v118, v162
	v_mul_f32_e32 v21, v119, v163
	v_add_f32_e32 v28, v20, v21
	v_mul_f32_e32 v20, v118, v164
	v_mul_f32_e32 v21, v119, v165
	v_add_f32_e32 v29, v20, v21
	v_mul_f32_e32 v20, v118, v166
	v_mul_f32_e32 v21, v119, v167
	v_add_f32_e32 v30, v20, v21
	v_mul_f32_e32 v20, v118, v168
	v_mul_f32_e32 v21, v119, v169
	v_add_f32_e32 v31, v20, v21
	v_mul_f32_e32 v20, v118, v170
	v_mul_f32_e32 v21, v119, v171
	v_add_f32_e32 v32, v20, v21
	v_mul_f32_e32 v20, v118, v172
	v_mul_f32_e32 v21, v119, v173
	v_add_f32_e32 v33, v20, v21
	v_mul_f32_e32 v20, v118, v174
	v_mul_f32_e32 v21, v119, v175
	v_add_f32_e32 v34, v20, v21
	v_mul_f32_e32 v20, v118, v176
	v_mul_f32_e32 v21, v119, v177
	v_add_f32_e32 v35, v20, v21
	v_mul_f32_e32 v20, v118, v178
	v_mul_f32_e32 v21, v119, v179
	v_add_f32_e32 v36, v20, v21
	v_mul_f32_e32 v20, v118, v180
	v_mul_f32_e32 v21, v119, v181
	v_add_f32_e32 v37, v20, v21
	v_cvt_pk_bf16_f32 v132, v22, v23
; __device__ __forceinline__ unsigned pk2(float lo, float hi) { typedef __bf16 bf16x2_t_ __attribute__((ext_vector_type(2))); f32x2 v = {lo, hi}; return __builtin_bit_cast(unsigned, __builtin_convertvector(v, bf16x2_t_)); }
; __device__ __forceinline__ f32x2 cmul(f32x2 a, f32x2 b) { return (f32x2){a.x * b.x - a.y * b.y, a.x * b.y + a.y * b.x}; }
; __global__ void __launch_bounds__(NTHR, 2) hymba_fwd(Params P) {
;     ...
;             bf16_t* w1 = W1 + (size_t)g * 256 * 256;
;             for (int idx = tid; idx < 256 * 128; idx += NTHR) { const int np = idx >> 7, k = (idx & 127) * 2; float v[2];
; #pragma unroll
;                 for (int e = 0; e < 2; ++e) { const int kk = k + e, s = kk >> 4, pp = kk & 15; float r = 0.f;
;                     if (np < 128) { const int n = np & 63; const f32x2 z = cmul(PW[(15 - s) * 64 + n], BBl[n * 16 + pp]); r = (np < 64) ? z.x : z.y; }
;                     v[e] = r; }
;                 *(unsigned*)(w1 + (size_t)np * 256 + k) = pk2(v[0], v[1]); }
	v_cvt_pk_bf16_f32 v133, v24, v25
	v_cvt_pk_bf16_f32 v134, v26, v27
	v_cvt_pk_bf16_f32 v135, v28, v29
	v_cvt_pk_bf16_f32 v136, v30, v31
	v_cvt_pk_bf16_f32 v137, v32, v33
	v_cvt_pk_bf16_f32 v138, v34, v35
	v_cvt_pk_bf16_f32 v139, v36, v37
	global_store_dwordx4 v18, v[132:135], s[14:15] offset:32
	global_store_dwordx4 v18, v[136:139], s[14:15] offset:48
	v_mul_f32_e32 v20, v120, v150
	v_mul_f32_e32 v21, v121, v151
	v_add_f32_e32 v22, v20, v21
	v_mul_f32_e32 v20, v120, v152
	v_mul_f32_e32 v21, v121, v153
	v_add_f32_e32 v23, v20, v21
	v_mul_f32_e32 v20, v120, v154
	v_mul_f32_e32 v21, v121, v155
	v_add_f32_e32 v24, v20, v21
	v_mul_f32_e32 v20, v120, v156
	v_mul_f32_e32 v21, v121, v157
	v_add_f32_e32 v25, v20, v21
	v_mul_f32_e32 v20, v120, v158
	v_mul_f32_e32 v21, v121, v159
	v_add_f32_e32 v26, v20, v21
	v_mul_f32_e32 v20, v120, v160
	v_mul_f32_e32 v21, v121, v161
	v_add_f32_e32 v27, v20, v21
	v_mul_f32_e32 v20, v120, v162
	v_mul_f32_e32 v21, v121, v163
	v_add_f32_e32 v28, v20, v21
	v_mul_f32_e32 v20, v120, v164
	v_mul_f32_e32 v21, v121, v165
	v_add_f32_e32 v29, v20, v21
	v_mul_f32_e32 v20, v120, v166
	v_mul_f32_e32 v21, v121, v167
	v_add_f32_e32 v30, v20, v21
	v_mul_f32_e32 v20, v120, v168
	v_mul_f32_e32 v21, v121, v169
	v_add_f32_e32 v31, v20, v21
	v_mul_f32_e32 v20, v120, v170
	v_mul_f32_e32 v21, v121, v171
	v_add_f32_e32 v32, v20, v21
	v_mul_f32_e32 v20, v120, v172
	v_mul_f32_e32 v21, v121, v173
	v_add_f32_e32 v33, v20, v21
	v_mul_f32_e32 v20, v120, v174
	v_mul_f32_e32 v21, v121, v175
	v_add_f32_e32 v34, v20, v21
	v_mul_f32_e32 v20, v120, v176
	v_mul_f32_e32 v21, v121, v177
	v_add_f32_e32 v35, v20, v21
	v_mul_f32_e32 v20, v120, v178
	v_mul_f32_e32 v21, v121, v179
	v_add_f32_e32 v36, v20, v21
	v_mul_f32_e32 v20, v120, v180
	v_mul_f32_e32 v21, v121, v181
	v_add_f32_e32 v37, v20, v21
	v_cvt_pk_bf16_f32 v132, v22, v23
	v_cvt_pk_bf16_f32 v133, v24, v25
	v_cvt_pk_bf16_f32 v134, v26, v27
	v_cvt_pk_bf16_f32 v135, v28, v29
	v_cvt_pk_bf16_f32 v136, v30, v31
	v_cvt_pk_bf16_f32 v137, v32, v33
	v_cvt_pk_bf16_f32 v138, v34, v35
	v_cvt_pk_bf16_f32 v139, v36, v37
	global_store_dwordx4 v18, v[132:135], s[14:15] offset:64
	global_store_dwordx4 v18, v[136:139], s[14:15] offset:80
	v_mul_f32_e32 v20, v122, v150
	v_mul_f32_e32 v21, v123, v151
	v_add_f32_e32 v22, v20, v21
	v_mul_f32_e32 v20, v122, v152
	v_mul_f32_e32 v21, v123, v153
	v_add_f32_e32 v23, v20, v21
	v_mul_f32_e32 v20, v122, v154
	v_mul_f32_e32 v21, v123, v155
	v_add_f32_e32 v24, v20, v21
	v_mul_f32_e32 v20, v122, v156
	v_mul_f32_e32 v21, v123, v157
	v_add_f32_e32 v25, v20, v21
	v_mul_f32_e32 v20, v122, v158
	v_mul_f32_e32 v21, v123, v159
	v_add_f32_e32 v26, v20, v21
	v_mul_f32_e32 v20, v122, v160
	v_mul_f32_e32 v21, v123, v161
	v_add_f32_e32 v27, v20, v21
	v_mul_f32_e32 v20, v122, v162
	v_mul_f32_e32 v21, v123, v163
	v_add_f32_e32 v28, v20, v21
	v_mul_f32_e32 v20, v122, v164
	v_mul_f32_e32 v21, v123, v165
	v_add_f32_e32 v29, v20, v21
	v_mul_f32_e32 v20, v122, v166
	v_mul_f32_e32 v21, v123, v167
	v_add_f32_e32 v30, v20, v21
	v_mul_f32_e32 v20, v122, v168
	v_mul_f32_e32 v21, v123, v169
	v_add_f32_e32 v31, v20, v21
	v_mul_f32_e32 v20, v122, v170
	v_mul_f32_e32 v21, v123, v171
	v_add_f32_e32 v32, v20, v21
	v_mul_f32_e32 v20, v122, v172
	v_mul_f32_e32 v21, v123, v173
	v_add_f32_e32 v33, v20, v21
	v_mul_f32_e32 v20, v122, v174
	v_mul_f32_e32 v21, v123, v175
	v_add_f32_e32 v34, v20, v21
	v_mul_f32_e32 v20, v122, v176
	v_mul_f32_e32 v21, v123, v177
	v_add_f32_e32 v35, v20, v21
	v_mul_f32_e32 v20, v122, v178
	v_mul_f32_e32 v21, v123, v179
	v_add_f32_e32 v36, v20, v21
	v_mul_f32_e32 v20, v122, v180
	v_mul_f32_e32 v21, v123, v181
	v_add_f32_e32 v37, v20, v21
	v_cvt_pk_bf16_f32 v132, v22, v23
	v_cvt_pk_bf16_f32 v133, v24, v25
	v_cvt_pk_bf16_f32 v134, v26, v27
	v_cvt_pk_bf16_f32 v135, v28, v29
	v_cvt_pk_bf16_f32 v136, v30, v31
	v_cvt_pk_bf16_f32 v137, v32, v33
	v_cvt_pk_bf16_f32 v138, v34, v35
	v_cvt_pk_bf16_f32 v139, v36, v37
	global_store_dwordx4 v18, v[132:135], s[14:15] offset:96
	global_store_dwordx4 v18, v[136:139], s[14:15] offset:112
	v_mul_f32_e32 v20, v124, v150
	v_mul_f32_e32 v21, v125, v151
	v_add_f32_e32 v22, v20, v21
	v_mul_f32_e32 v20, v124, v152
	v_mul_f32_e32 v21, v125, v153
	v_add_f32_e32 v23, v20, v21
	v_mul_f32_e32 v20, v124, v154
	v_mul_f32_e32 v21, v125, v155
	v_add_f32_e32 v24, v20, v21
	v_mul_f32_e32 v20, v124, v156
	v_mul_f32_e32 v21, v125, v157
	v_add_f32_e32 v25, v20, v21
	v_mul_f32_e32 v20, v124, v158
	v_mul_f32_e32 v21, v125, v159
	v_add_f32_e32 v26, v20, v21
	v_mul_f32_e32 v20, v124, v160
	v_mul_f32_e32 v21, v125, v161
	v_add_f32_e32 v27, v20, v21
	v_mul_f32_e32 v20, v124, v162
	v_mul_f32_e32 v21, v125, v163
	v_add_f32_e32 v28, v20, v21
	v_mul_f32_e32 v20, v124, v164
	v_mul_f32_e32 v21, v125, v165
	v_add_f32_e32 v29, v20, v21
	v_mul_f32_e32 v20, v124, v166
	v_mul_f32_e32 v21, v125, v167
	v_add_f32_e32 v30, v20, v21
	v_mul_f32_e32 v20, v124, v168
	v_mul_f32_e32 v21, v125, v169
	v_add_f32_e32 v31, v20, v21
	v_mul_f32_e32 v20, v124, v170
	v_mul_f32_e32 v21, v125, v171
	v_add_f32_e32 v32, v20, v21
	v_mul_f32_e32 v20, v124, v172
	v_mul_f32_e32 v21, v125, v173
	v_add_f32_e32 v33, v20, v21
	v_mul_f32_e32 v20, v124, v174
	v_mul_f32_e32 v21, v125, v175
	v_add_f32_e32 v34, v20, v21
	v_mul_f32_e32 v20, v124, v176
	v_mul_f32_e32 v21, v125, v177
	v_add_f32_e32 v35, v20, v21
	v_mul_f32_e32 v20, v124, v178
	v_mul_f32_e32 v21, v125, v179
	v_add_f32_e32 v36, v20, v21
	v_mul_f32_e32 v20, v124, v180
	v_mul_f32_e32 v21, v125, v181
	v_add_f32_e32 v37, v20, v21
	v_cvt_pk_bf16_f32 v132, v22, v23
	v_cvt_pk_bf16_f32 v133, v24, v25
	v_cvt_pk_bf16_f32 v134, v26, v27
	v_cvt_pk_bf16_f32 v135, v28, v29
; __device__ __forceinline__ unsigned pk2(float lo, float hi) { typedef __bf16 bf16x2_t_ __attribute__((ext_vector_type(2))); f32x2 v = {lo, hi}; return __builtin_bit_cast(unsigned, __builtin_convertvector(v, bf16x2_t_)); }
; __device__ __forceinline__ f32x2 cmul(f32x2 a, f32x2 b) { return (f32x2){a.x * b.x - a.y * b.y, a.x * b.y + a.y * b.x}; }
; __global__ void __launch_bounds__(NTHR, 2) hymba_fwd(Params P) {
;     ...
;             bf16_t* w1 = W1 + (size_t)g * 256 * 256;
;             for (int idx = tid; idx < 256 * 128; idx += NTHR) { const int np = idx >> 7, k = (idx & 127) * 2; float v[2];
; #pragma unroll
;                 for (int e = 0; e < 2; ++e) { const int kk = k + e, s = kk >> 4, pp = kk & 15; float r = 0.f;
;                     if (np < 128) { const int n = np & 63; const f32x2 z = cmul(PW[(15 - s) * 64 + n], BBl[n * 16 + pp]); r = (np < 64) ? z.x : z.y; }
;                     v[e] = r; }
;                 *(unsigned*)(w1 + (size_t)np * 256 + k) = pk2(v[0], v[1]); }
	v_cvt_pk_bf16_f32 v136, v30, v31
	v_cvt_pk_bf16_f32 v137, v32, v33
	v_cvt_pk_bf16_f32 v138, v34, v35
	v_cvt_pk_bf16_f32 v139, v36, v37
	global_store_dwordx4 v18, v[132:135], s[14:15] offset:128
	global_store_dwordx4 v18, v[136:139], s[14:15] offset:144
	v_mul_f32_e32 v20, v126, v150
	v_mul_f32_e32 v21, v127, v151
	v_add_f32_e32 v22, v20, v21
	v_mul_f32_e32 v20, v126, v152
	v_mul_f32_e32 v21, v127, v153
	v_add_f32_e32 v23, v20, v21
	v_mul_f32_e32 v20, v126, v154
	v_mul_f32_e32 v21, v127, v155
	v_add_f32_e32 v24, v20, v21
	v_mul_f32_e32 v20, v126, v156
	v_mul_f32_e32 v21, v127, v157
	v_add_f32_e32 v25, v20, v21
	v_mul_f32_e32 v20, v126, v158
	v_mul_f32_e32 v21, v127, v159
	v_add_f32_e32 v26, v20, v21
	v_mul_f32_e32 v20, v126, v160
	v_mul_f32_e32 v21, v127, v161
	v_add_f32_e32 v27, v20, v21
	v_mul_f32_e32 v20, v126, v162
	v_mul_f32_e32 v21, v127, v163
	v_add_f32_e32 v28, v20, v21
	v_mul_f32_e32 v20, v126, v164
	v_mul_f32_e32 v21, v127, v165
	v_add_f32_e32 v29, v20, v21
	v_mul_f32_e32 v20, v126, v166
	v_mul_f32_e32 v21, v127, v167
	v_add_f32_e32 v30, v20, v21
	v_mul_f32_e32 v20, v126, v168
	v_mul_f32_e32 v21, v127, v169
	v_add_f32_e32 v31, v20, v21
	v_mul_f32_e32 v20, v126, v170
	v_mul_f32_e32 v21, v127, v171
	v_add_f32_e32 v32, v20, v21
	v_mul_f32_e32 v20, v126, v172
	v_mul_f32_e32 v21, v127, v173
	v_add_f32_e32 v33, v20, v21
	v_mul_f32_e32 v20, v126, v174
	v_mul_f32_e32 v21, v127, v175
	v_add_f32_e32 v34, v20, v21
	v_mul_f32_e32 v20, v126, v176
	v_mul_f32_e32 v21, v127, v177
	v_add_f32_e32 v35, v20, v21
	v_mul_f32_e32 v20, v126, v178
	v_mul_f32_e32 v21, v127, v179
	v_add_f32_e32 v36, v20, v21
	v_mul_f32_e32 v20, v126, v180
	v_mul_f32_e32 v21, v127, v181
	v_add_f32_e32 v37, v20, v21
	v_cvt_pk_bf16_f32 v132, v22, v23
	v_cvt_pk_bf16_f32 v133, v24, v25
	v_cvt_pk_bf16_f32 v134, v26, v27
	v_cvt_pk_bf16_f32 v135, v28, v29
	v_cvt_pk_bf16_f32 v136, v30, v31
	v_cvt_pk_bf16_f32 v137, v32, v33
	v_cvt_pk_bf16_f32 v138, v34, v35
	v_cvt_pk_bf16_f32 v139, v36, v37
	global_store_dwordx4 v18, v[132:135], s[14:15] offset:160
	global_store_dwordx4 v18, v[136:139], s[14:15] offset:176
	v_mul_f32_e32 v20, v128, v150
	v_mul_f32_e32 v21, v129, v151
	v_add_f32_e32 v22, v20, v21
	v_mul_f32_e32 v20, v128, v152
	v_mul_f32_e32 v21, v129, v153
	v_add_f32_e32 v23, v20, v21
	v_mul_f32_e32 v20, v128, v154
	v_mul_f32_e32 v21, v129, v155
	v_add_f32_e32 v24, v20, v21
	v_mul_f32_e32 v20, v128, v156
	v_mul_f32_e32 v21, v129, v157
	v_add_f32_e32 v25, v20, v21
	v_mul_f32_e32 v20, v128, v158
	v_mul_f32_e32 v21, v129, v159
	v_add_f32_e32 v26, v20, v21
	v_mul_f32_e32 v20, v128, v160
	v_mul_f32_e32 v21, v129, v161
	v_add_f32_e32 v27, v20, v21
	v_mul_f32_e32 v20, v128, v162
	v_mul_f32_e32 v21, v129, v163
	v_add_f32_e32 v28, v20, v21
	v_mul_f32_e32 v20, v128, v164
	v_mul_f32_e32 v21, v129, v165
	v_add_f32_e32 v29, v20, v21
	v_mul_f32_e32 v20, v128, v166
	v_mul_f32_e32 v21, v129, v167
	v_add_f32_e32 v30, v20, v21
	v_mul_f32_e32 v20, v128, v168
	v_mul_f32_e32 v21, v129, v169
	v_add_f32_e32 v31, v20, v21
	v_mul_f32_e32 v20, v128, v170
	v_mul_f32_e32 v21, v129, v171
	v_add_f32_e32 v32, v20, v21
	v_mul_f32_e32 v20, v128, v172
	v_mul_f32_e32 v21, v129, v173
	v_add_f32_e32 v33, v20, v21
	v_mul_f32_e32 v20, v128, v174
	v_mul_f32_e32 v21, v129, v175
	v_add_f32_e32 v34, v20, v21
	v_mul_f32_e32 v20, v128, v176
	v_mul_f32_e32 v21, v129, v177
	v_add_f32_e32 v35, v20, v21
	v_mul_f32_e32 v20, v128, v178
	v_mul_f32_e32 v21, v129, v179
	v_add_f32_e32 v36, v20, v21
	v_mul_f32_e32 v20, v128, v180
	v_mul_f32_e32 v21, v129, v181
	v_add_f32_e32 v37, v20, v21
	v_cvt_pk_bf16_f32 v132, v22, v23
	v_cvt_pk_bf16_f32 v133, v24, v25
	v_cvt_pk_bf16_f32 v134, v26, v27
	v_cvt_pk_bf16_f32 v135, v28, v29
	v_cvt_pk_bf16_f32 v136, v30, v31
	v_cvt_pk_bf16_f32 v137, v32, v33
	v_cvt_pk_bf16_f32 v138, v34, v35
	v_cvt_pk_bf16_f32 v139, v36, v37
	global_store_dwordx4 v18, v[132:135], s[14:15] offset:192
	global_store_dwordx4 v18, v[136:139], s[14:15] offset:208
	v_mul_f32_e32 v20, v130, v150
	v_mul_f32_e32 v21, v131, v151
	v_add_f32_e32 v22, v20, v21
	v_mul_f32_e32 v20, v130, v152
	v_mul_f32_e32 v21, v131, v153
	v_add_f32_e32 v23, v20, v21
	v_mul_f32_e32 v20, v130, v154
	v_mul_f32_e32 v21, v131, v155
	v_add_f32_e32 v24, v20, v21
	v_mul_f32_e32 v20, v130, v156
	v_mul_f32_e32 v21, v131, v157
	v_add_f32_e32 v25, v20, v21
	v_mul_f32_e32 v20, v130, v158
	v_mul_f32_e32 v21, v131, v159
	v_add_f32_e32 v26, v20, v21
	v_mul_f32_e32 v20, v130, v160
	v_mul_f32_e32 v21, v131, v161
	v_add_f32_e32 v27, v20, v21
	v_mul_f32_e32 v20, v130, v162
	v_mul_f32_e32 v21, v131, v163
	v_add_f32_e32 v28, v20, v21
	v_mul_f32_e32 v20, v130, v164
	v_mul_f32_e32 v21, v131, v165
	v_add_f32_e32 v29, v20, v21
	v_mul_f32_e32 v20, v130, v166
	v_mul_f32_e32 v21, v131, v167
	v_add_f32_e32 v30, v20, v21
	v_mul_f32_e32 v20, v130, v168
	v_mul_f32_e32 v21, v131, v169
	v_add_f32_e32 v31, v20, v21
	v_mul_f32_e32 v20, v130, v170
	v_mul_f32_e32 v21, v131, v171
	v_add_f32_e32 v32, v20, v21
	v_mul_f32_e32 v20, v130, v172
	v_mul_f32_e32 v21, v131, v173
	v_add_f32_e32 v33, v20, v21
	v_mul_f32_e32 v20, v130, v174
	v_mul_f32_e32 v21, v131, v175
	v_add_f32_e32 v34, v20, v21
	v_mul_f32_e32 v20, v130, v176
	v_mul_f32_e32 v21, v131, v177
	v_add_f32_e32 v35, v20, v21
	v_mul_f32_e32 v20, v130, v178
	v_mul_f32_e32 v21, v131, v179
	v_add_f32_e32 v36, v20, v21
	v_mul_f32_e32 v20, v130, v180
	v_mul_f32_e32 v21, v131, v181
	v_add_f32_e32 v37, v20, v21
	v_cvt_pk_bf16_f32 v132, v22, v23
	v_cvt_pk_bf16_f32 v133, v24, v25
	v_cvt_pk_bf16_f32 v134, v26, v27
	v_cvt_pk_bf16_f32 v135, v28, v29
	v_cvt_pk_bf16_f32 v136, v30, v31
	v_cvt_pk_bf16_f32 v137, v32, v33
	v_cvt_pk_bf16_f32 v138, v34, v35
	v_cvt_pk_bf16_f32 v139, v36, v37
	global_store_dwordx4 v18, v[132:135], s[14:15] offset:224
	global_store_dwordx4 v18, v[136:139], s[14:15] offset:240
